# static priority raise for waves 4..7 during the SSD triangular M block (reset at the M barrier)
# speedup vs baseline: 1.0047x; 1.0021x over previous
.LBB0_35:
	s_mov_b32 s44, 0
	s_add_i32 s2, s44, s76
	s_waitcnt vmcnt(0)
	v_mbcnt_lo_u32_b32 v0, -1, 0
	v_mbcnt_hi_u32_b32 v0, -1, v0
	s_add_i32 s18, s44, s69
	v_lshl_add_u32 v176, s2, 6, v0
	s_add_i32 s82, s44, s72
	v_readfirstlane_b32 s2, v176
	s_ashr_i32 s6, s2, 6
	v_readlane_b32 s4, v254, 11
	s_cmp_gt_u32 s4, 16
	s_cselect_b64 s[2:3], -1, 0
	s_cmp_lt_u32 s4, 17
	s_cselect_b64 s[10:11], -1, 0
	s_and_b64 s[4:5], s[10:11], exec
	s_mov_b32 s4, 0x12000
	s_cselect_b32 s4, s4, 0x10000
	s_lshl_b32 s5, s82, 3
	s_abs_i32 s7, s5
	v_cvt_f32_u32_e32 v1, s7
	s_mov_b32 s14, s18
	v_writelane_b32 v254, s14, 41
	s_lshl_b32 s13, s18, 3
	v_rcp_iflag_f32_e32 v1, v1
	v_writelane_b32 v254, s15, 42
	s_add_i32 s6, s6, s13
	s_sub_i32 s13, 0, s7
	v_mul_f32_e32 v1, 0x4f7ffffe, v1
	v_cvt_u32_f32_e32 v1, v1
	s_add_i32 s12, s4, s5
	s_add_i32 s12, s12, -1
	s_xor_b32 s5, s12, s5
	v_readfirstlane_b32 s14, v1
	s_mul_i32 s13, s13, s14
	s_mul_hi_u32 s13, s14, s13
	s_abs_i32 s12, s12
	s_add_i32 s14, s14, s13
	s_mul_hi_u32 s13, s12, s14
	s_mul_i32 s14, s13, s7
	s_sub_i32 s12, s12, s14
	s_ashr_i32 s5, s5, 31
	s_add_i32 s14, s13, 1
	s_sub_i32 s15, s12, s7
	s_cmp_ge_u32 s12, s7
	s_cselect_b32 s13, s14, s13
	s_cselect_b32 s12, s15, s12
	s_add_i32 s14, s13, 1
	s_cmp_ge_u32 s12, s7
	s_cselect_b32 s7, s14, s13
	s_xor_b32 s7, s7, s5
	s_sub_i32 s5, s7, s5
	s_mul_i32 s56, s5, s6
	s_add_i32 s5, s56, s5
	s_min_i32 s57, s5, s4
	s_cmp_ge_i32 s56, s57
	s_mov_b32 s54, 0x800000
	s_cbranch_scc1 .LBB0_134
	v_readlane_b32 s28, v254, 11
	s_cmp_lg_u32 s28, 21
	s_cselect_b64 s[6:7], -1, 0
	s_cmp_eq_u32 s28, 21
	s_cselect_b64 s[12:13], -1, 0
	s_cmp_eq_u32 s28, 17
	s_cselect_b64 s[14:15], -1, 0
	s_lshl_b64 s[4:5], s[44:45], 3
	s_add_u32 s22, s70, s4
	v_readlane_b32 s24, v253, 62
	s_addc_u32 s23, s71, s5
	v_readlane_b32 s26, v254, 0
	v_readlane_b32 s27, v254, 1
	s_add_u32 s4, s26, s44
	s_addc_u32 s5, s27, 0
	s_lshl_b64 s[18:19], s[44:45], 2
	v_readlane_b32 s25, v253, 63
	s_add_u32 s58, s24, s18
	s_addc_u32 s59, s25, s19
	s_cmp_eq_u32 s28, 10
	s_cselect_b64 s[18:19], -1, 0
	s_and_b64 s[20:21], s[18:19], exec
	s_movk_i32 s20, 0x400
	s_cselect_b32 s60, s20, 0x1000
	s_cselect_b32 s61, 0, 0xc00
	s_or_b64 s[12:13], s[18:19], s[12:13]
	s_and_b64 s[18:19], s[12:13], exec
	s_cselect_b32 s18, 64, 48
	s_add_u32 s18, s22, s18
	s_addc_u32 s19, s23, 0
	s_load_dwordx2 s[18:19], s[18:19], 0x0
	s_and_b64 s[10:11], s[10:11], exec
	s_cselect_b32 s20, 0, 0x1000
	v_and_b32_e32 v34, 63, v0
	v_lshlrev_b32_e32 v192, 5, v34
	s_waitcnt lgkmcnt(0)
	s_add_u32 s10, s18, s20
	s_addc_u32 s11, s19, 0
	s_and_b64 s[12:13], s[12:13], exec
	s_cselect_b32 s12, 0x48, 56
	s_add_u32 s12, s22, s12
	s_addc_u32 s13, s23, 0
	s_load_dwordx2 s[12:13], s[12:13], 0x0
	v_xor_b32_e32 v32, 1, v229
	v_cmp_lt_i32_e32 vcc, v32, v231
	v_mov_b32_e32 v33, v193
	v_mov_b32_e32 v62, 0
	s_waitcnt lgkmcnt(0)
	s_add_u32 s12, s12, s20
	s_addc_u32 s13, s13, 0
	global_load_dwordx4 v[0:3], v192, s[10:11] offset:16
	global_load_dwordx4 v[4:7], v192, s[10:11]
	global_load_dwordx4 v[8:11], v192, s[12:13] offset:16
	global_load_dwordx4 v[12:15], v192, s[12:13]
	global_load_dwordx4 v[16:19], v192, s[10:11] offset:2064
	global_load_dwordx4 v[20:23], v192, s[10:11] offset:2048
	global_load_dwordx4 v[24:27], v192, s[12:13] offset:2064
	global_load_dwordx4 v[28:31], v192, s[12:13] offset:2048
	v_cndmask_b32_e32 v32, v229, v32, vcc
	v_lshlrev_b32_e32 v109, 2, v32
	v_xor_b32_e32 v32, 2, v229
	v_cmp_lt_i32_e32 vcc, v32, v231
	s_cmp_eq_u32 s28, 6
	s_cselect_b64 s[10:11], -1, 0
	v_cndmask_b32_e32 v32, v229, v32, vcc
	v_lshlrev_b32_e32 v121, 2, v32
	v_xor_b32_e32 v32, 4, v229
	v_cmp_lt_i32_e32 vcc, v32, v231
	s_and_b64 s[12:13], s[10:11], exec
	s_mov_b32 s12, 0x44d4000
	v_cndmask_b32_e32 v32, v229, v32, vcc
	v_lshlrev_b32_e32 v122, 2, v32
	v_xor_b32_e32 v32, 8, v229
	v_cmp_lt_i32_e32 vcc, v32, v231
	s_cselect_b32 s12, s12, 0x459a000
	s_or_b64 s[10:11], s[10:11], s[14:15]
	v_cndmask_b32_e32 v32, v229, v32, vcc
	v_lshlrev_b32_e32 v123, 2, v32
	v_xor_b32_e32 v32, 16, v229
	v_cmp_lt_i32_e32 vcc, v32, v231
	s_add_u32 s62, s4, 0x38260000
	s_addc_u32 s63, s5, 0
	v_cndmask_b32_e32 v32, v229, v32, vcc
	v_lshlrev_b32_e32 v124, 2, v32
	v_xor_b32_e32 v32, 32, v229
	s_add_u32 s64, s4, 0x3d2e4000
	v_cmp_lt_i32_e32 vcc, v32, v231
	s_addc_u32 s65, s5, 0
	s_add_u32 s14, s4, s12
	v_cndmask_b32_e32 v32, v229, v32, vcc
	v_lshlrev_b32_e32 v125, 2, v32
	v_lshlrev_b32_e32 v32, 4, v34
	s_addc_u32 s15, s5, 0
	v_lshl_add_u64 v[32:33], s[4:5], 0, v[32:33]
	s_mov_b64 s[4:5], 0x4660000
	v_lshl_add_u64 v[110:111], v[32:33], 0, s[4:5]
	v_cmp_eq_u32_e32 vcc, 0, v34
	s_mov_b64 s[4:5], 0x16660000
	v_lshlrev_b32_e32 v108, 3, v34
	s_mov_b32 s68, -1
	s_and_b64 s[12:13], s[6:7], vcc
	v_lshl_add_u64 v[112:113], s[14:15], 0, v[192:193]
	v_lshl_add_u64 v[114:115], v[32:33], 0, s[4:5]
	v_mov_b32_e32 v63, v62
	v_mov_b32_e32 v54, v62
	v_mov_b32_e32 v55, v62
	v_mov_b32_e32 v60, v62
	v_mov_b32_e32 v61, v62
	v_mov_b32_e32 v52, v62
	v_mov_b32_e32 v53, v62
	v_mov_b32_e32 v58, v62
	v_mov_b32_e32 v59, v62
	v_mov_b32_e32 v50, v62
	v_mov_b32_e32 v51, v62
	v_mov_b32_e32 v56, v62
	v_mov_b32_e32 v57, v62
	v_mov_b32_e32 v48, v62
	v_mov_b32_e32 v49, v62
	v_mov_b32_e32 v38, v62
	v_mov_b32_e32 v39, v62
	v_mov_b32_e32 v46, v62
	v_mov_b32_e32 v47, v62
	v_mov_b32_e32 v36, v62
	v_mov_b32_e32 v37, v62
	v_mov_b32_e32 v44, v62
	v_mov_b32_e32 v45, v62
	v_mov_b32_e32 v34, v62
	v_mov_b32_e32 v35, v62
	v_mov_b32_e32 v42, v62
	v_mov_b32_e32 v43, v62
	v_mov_b32_e32 v32, v62
	v_mov_b32_e32 v33, v62
	v_mov_b32_e32 v40, v62
	v_mov_b32_e32 v41, v62
	s_branch .LBB0_38
	s_nop 0
	s_nop 0
	s_nop 0
	s_nop 0
	s_nop 0
	s_nop 0
	s_nop 0
	s_nop 0
	s_nop 0
.LBB0_37:
	s_add_i32 s56, s56, 4
	s_cmp_ge_i32 s56, s57
	s_cbranch_scc1 .LBB0_134

.Lssd_pf_done:
	s_cbranch_vccz .LBB0_208
	v_readfirstlane_b32 s98, v176
	s_nop 3
	s_lshr_b32 s98, s98, 6
	s_cmp_gt_u32 s98, 3
	s_cbranch_scc0 .Lssd_prio_skip
	s_setprio 1
.Lssd_prio_skip:
	ds_read_b32 v80, v97
	ds_read_b128 v[60:63], v186
	ds_read_b128 v[56:59], v187
	ds_read_b128 v[52:55], v188
	ds_read_b128 v[48:51], v189
	v_mov_b32_e32 v65, 0
	s_andn2_b64 vcc, exec, s[2:3]
	v_add_u32_e32 v75, 0, v108
	v_add_u32_e32 v74, 0, v109
	v_add_u32_e32 v73, 0, v110
	v_add_u32_e32 v72, 0, v111
	v_mov_b32_e32 v67, 0
	v_mov_b32_e32 v66, 0
	s_cbranch_vccnz .LBB0_277
	ds_read_b128 v[216:219], v75 offset:32768
	ds_read_b128 v[220:223], v74 offset:32768
	ds_read_b128 v[232:235], v73 offset:32768
	ds_read_b128 v[246:249], v72 offset:32768
	ds_read_b128 v[76:79], v112
	ds_read_b128 v[82:85], v113
	v_readlane_b32 s34, v254, 51
	v_readlane_b32 s35, v254, 52
	s_waitcnt lgkmcnt(5)
	v_mfma_f32_16x16x32_bf16 v[66:69], v[216:219], v[60:63], 0
	s_waitcnt lgkmcnt(4)
	v_mfma_f32_16x16x32_bf16 v[66:69], v[220:223], v[56:59], v[66:69]
	s_waitcnt lgkmcnt(3)
	v_mfma_f32_16x16x32_bf16 v[66:69], v[232:235], v[52:55], v[66:69]
	s_waitcnt lgkmcnt(2)
	v_mfma_f32_16x16x32_bf16 v[66:69], v[246:249], v[48:51], v[66:69]
	s_waitcnt lgkmcnt(1)
	v_sub_f32_e32 v64, v80, v76
	v_mul_f32_e32 v64, 0x3fb8aa3b, v64
	v_exp_f32_e32 v64, v64
	s_nop 1
	v_mul_f32_e32 v64, v66, v64
	v_sub_f32_e32 v66, v80, v77
	v_mul_f32_e32 v66, 0x3fb8aa3b, v66
	v_exp_f32_e32 v66, v66
	s_waitcnt lgkmcnt(0)
	v_mul_f32_e32 v64, v82, v64
	v_cndmask_b32_e64 v64, v64, 0, s[34:35]
	v_readlane_b32 s34, v254, 47
	v_mul_f32_e32 v66, v67, v66
	v_mul_f32_e32 v66, v83, v66
	v_readlane_b32 s35, v254, 48
	v_sub_f32_e32 v67, v80, v79
	v_mul_f32_e32 v67, 0x3fb8aa3b, v67
	v_cndmask_b32_e64 v70, 0, v66, s[34:35]
	v_sub_f32_e32 v66, v80, v78
	v_mul_f32_e32 v66, 0x3fb8aa3b, v66
	v_exp_f32_e32 v66, v66
	v_exp_f32_e32 v67, v67
	v_readlane_b32 s34, v254, 45
	v_readlane_b32 s35, v254, 46
	v_pk_mul_f32 v[66:67], v[68:69], v[66:67]
	s_nop 0
	v_pk_mul_f32 v[68:69], v[84:85], v[66:67]
	v_cvt_pk_bf16_f32 v66, v64, v70
	v_cvt_pk_bf16_f32 v64, v68, v69
	v_cndmask_b32_e64 v67, v64, 0, s[34:35]
	v_readlane_b32 s34, v254, 43
	v_lshrrev_b32_e32 v64, 16, v64
	v_readlane_b32 s35, v254, 44
	s_nop 1
	v_cndmask_b32_e64 v64, v64, 0, s[34:35]
	s_mov_b32 s34, 0x5040100
	v_perm_b32 v67, v64, v67, s34

.LBB0_289:
	s_waitcnt lgkmcnt(4)
	v_mul_f32_e32 v80, 0x3fb8aa3b, v80
	v_exp_f32_e32 v89, v80
	v_add_u32_e32 v80, s17, v108
	s_setprio 0
	s_waitcnt lgkmcnt(0)
	s_barrier
	ds_write_b64 v160, v[66:67] offset:32768
	ds_write_b64 v161, v[64:65] offset:32768
	ds_write_b64 v162, v[70:71] offset:32768
	ds_write_b64 v163, v[68:69] offset:32768
	ds_write_b64 v164, v[74:75] offset:32768
	ds_write_b64 v165, v[72:73] offset:32768
	ds_write_b64 v166, v[76:77] offset:32768
	ds_write_b64 v167, v[78:79] offset:32768
	s_waitcnt lgkmcnt(0)
	s_barrier
	ds_read_b128 v[76:79], v186 offset:32768
	ds_read_b128 v[72:75], v187 offset:32768
	ds_read_b128 v[68:71], v188 offset:32768
	ds_read_b128 v[64:67], v189 offset:32768
	ds_read_u16 v236, v168
	ds_read_u16 v237, v169
	ds_read_u16 v242, v170
	ds_read_u16 v243, v171
	ds_read_b128 v[216:219], v80
	v_add_u32_e32 v90, s66, v108
	ds_read_b128 v[220:223], v90
	v_add_u32_e32 v90, s17, v109
	ds_read_b128 v[232:235], v90
	v_add_u32_e32 v90, s66, v109
	ds_read_b128 v[246:249], v90
	v_add_u32_e32 v90, s17, v110
	ds_read_b128 v[202:205], v90
	v_add_u32_e32 v90, s66, v110
	ds_read_b128 v[206:209], v90
	s_andn2_b64 vcc, exec, s[30:31]
	s_waitcnt lgkmcnt(5)
	v_mfma_f32_16x16x32_bf16 v[80:83], v[216:219], v[76:79], 0
	v_add_u32_e32 v90, s17, v111
	ds_read_b128 v[216:219], v90
	s_waitcnt lgkmcnt(5)
	v_mfma_f32_16x16x32_bf16 v[84:87], v[220:223], v[60:63], 0
	v_add_u32_e32 v90, s66, v111
	ds_read_b128 v[220:223], v90
	s_waitcnt lgkmcnt(5)
	v_mfma_f32_16x16x32_bf16 v[80:83], v[232:235], v[72:75], v[80:83]
	s_waitcnt lgkmcnt(4)
	v_mfma_f32_16x16x32_bf16 v[84:87], v[246:249], v[56:59], v[84:87]
	s_waitcnt lgkmcnt(3)
	v_mfma_f32_16x16x32_bf16 v[80:83], v[202:205], v[68:71], v[80:83]
	s_waitcnt lgkmcnt(2)
	v_mfma_f32_16x16x32_bf16 v[84:87], v[206:209], v[52:55], v[84:87]
	s_waitcnt lgkmcnt(1)
	v_mfma_f32_16x16x32_bf16 v[80:83], v[216:219], v[64:67], v[80:83]
	s_waitcnt lgkmcnt(0)
	v_mfma_f32_16x16x32_bf16 v[84:87], v[220:223], v[48:51], v[84:87]
	s_nop 7
	v_fma_f32 v80, v89, v84, v80
	v_cndmask_b32_e64 v84, 0, 1, s[30:31]
	v_cmp_ne_u32_e64 s[34:35], 1, v84
	s_cbranch_vccnz .LBB0_297
	v_lshlrev_b32_e32 v84, 16, v236
	s_waitcnt vmcnt(0)
	v_fmac_f32_e32 v80, v200, v84
	s_and_b64 vcc, exec, s[34:35]
	v_fma_f32 v81, v89, v85, v81
	s_cbranch_vccz .LBB0_298
